# v10 plus hand-scheduled VALU gdot loops (placeholder load now targets a never-read register)
# speedup vs baseline: 1.0110x; 1.0002x over previous
.LBB0_532:
	s_or_b64 exec, exec, s[0:1]
	s_waitcnt lgkmcnt(0)
	v_mov_b32_e32 v0, v178
	s_and_b32 s5, s88, -8
	s_barrier
	s_and_b32 s4, s88, 7
	v_ashrrev_i32_e32 v1, 6, v0
	v_writelane_b32 v255, s5, 3
	v_add_u32_e32 v152, s5, v1
	s_lshl_b32 s92, s4, 14
	v_writelane_b32 v255, s4, 4
	s_lshl_b32 s4, s4, 21
	s_movk_i32 s16, 0x4000
	s_mov_b64 s[2:3], 0
	s_mov_b64 s[0:1], 0
	s_and_b32 s89, s90, -8
	s_mov_b32 s93, 0
	v_writelane_b32 v255, s4, 5
	v_cmp_gt_i32_e32 vcc, s16, v152
	s_and_saveexec_b64 s[10:11], vcc
	s_cbranch_execz .LBB0_541
	v_readlane_b32 s0, v254, 0
	v_readlane_b32 s1, v254, 1
	v_readlane_b32 s34, v255, 4
	s_lshl_b32 s35, s34, 21
	s_add_u32 s2, s0, 0x2120000
	s_addc_u32 s3, s1, 0
	s_add_u32 s2, s2, s35
	s_addc_u32 s3, s3, 0
	v_readlane_b32 s4, v254, 39
	v_readlane_b32 s5, v254, 40
	s_lshl_b32 s35, s34, 9
	s_add_u32 s4, s4, s35
	s_addc_u32 s5, s5, 0
	s_add_u32 s6, s0, 0x19d20000
	s_addc_u32 s7, s1, 0
	s_lshl_b32 s35, s34, 23
	s_add_u32 s12, s0, 0x10120000
	s_addc_u32 s13, s1, 0
	s_add_u32 s12, s12, s35
	s_addc_u32 s13, s13, 0
	v_readfirstlane_b32 s20, v178
	s_lshr_b32 s20, s20, 6
	v_readlane_b32 s35, v255, 3
	s_add_u32 s20, s20, s35
	s_and_b32 s21, s90, -8
	v_and_b32_e32 v176, 7, v179
	v_lshlrev_b32_e32 v177, 6, v176
	v_lshlrev_b32_e32 v176, 4, v176
	v_lshlrev_b32_e32 v180, 3, v179
	v_lshrrev_b32_e32 v181, 3, v179
	v_lshlrev_b32_e32 v181, 6, v181
	s_mov_b32 s26, 0xcccccccc
	s_mov_b32 s27, 0xcccccccc
	s_mov_b32 s28, 0xaaaaaaaa
	s_mov_b32 s29, 0xaaaaaaaa
	s_lshl_b32 s34, s20, 9
	s_add_u32 s22, s6, s34
	s_addc_u32 s23, s7, 0
	global_load_dwordx4 v[160:163], v181, s[22:23] offset:0
	global_load_dwordx4 v[164:167], v181, s[22:23] offset:16
	global_load_dwordx4 v[168:171], v181, s[22:23] offset:32
	global_load_dwordx4 v[172:175], v181, s[22:23] offset:48
	s_add_u32 s36, s20, s21
	s_min_u32 s36, s36, 0x3fff
	s_lshl_b32 s34, s36, 9
	s_add_u32 s22, s6, s34
	s_addc_u32 s23, s7, 0
	global_load_dwordx4 v[186:189], v181, s[22:23] offset:0
	global_load_dwordx4 v[190:193], v181, s[22:23] offset:16
	global_load_dwordx4 v[194:197], v181, s[22:23] offset:32
	global_load_dwordx4 v[198:201], v181, s[22:23] offset:48
	s_waitcnt vmcnt(0)
	v_lshl_or_b32 v160, v160, 7, v176
	v_lshl_or_b32 v161, v161, 7, v176
	v_lshl_or_b32 v162, v162, 7, v176
	v_lshl_or_b32 v163, v163, 7, v176
	v_lshl_or_b32 v164, v164, 7, v176
	v_lshl_or_b32 v165, v165, 7, v176
	v_lshl_or_b32 v166, v166, 7, v176
	v_lshl_or_b32 v167, v167, 7, v176
	v_lshl_or_b32 v168, v168, 7, v176
	v_lshl_or_b32 v169, v169, 7, v176
	v_lshl_or_b32 v170, v170, 7, v176
	v_lshl_or_b32 v171, v171, 7, v176
	v_lshl_or_b32 v172, v172, 7, v176
	v_lshl_or_b32 v173, v173, 7, v176
	v_lshl_or_b32 v174, v174, 7, v176
	v_lshl_or_b32 v175, v175, 7, v176
	s_lshl_b32 s34, s20, 12
	s_add_u32 s24, s4, s34
	s_addc_u32 s25, s5, 0
	global_load_dwordx4 v[128:131], v177, s[24:25] offset:0
	global_load_dwordx4 v[132:135], v177, s[24:25] offset:16
	global_load_dwordx4 v[136:139], v177, s[24:25] offset:32
	global_load_dwordx4 v[140:143], v177, s[24:25] offset:48
	global_load_dwordx4 v[0:3], v160, s[2:3]
	global_load_dwordx4 v[4:7], v161, s[2:3]
	global_load_dwordx4 v[8:11], v162, s[2:3]
	global_load_dwordx4 v[12:15], v163, s[2:3]
	global_load_dwordx4 v[16:19], v164, s[2:3]
	global_load_dwordx4 v[20:23], v165, s[2:3]
	global_load_dwordx4 v[24:27], v166, s[2:3]
	global_load_dwordx4 v[28:31], v167, s[2:3]
	global_load_dwordx4 v[32:35], v168, s[2:3]
	global_load_dwordx4 v[36:39], v169, s[2:3]
	global_load_dwordx4 v[40:43], v170, s[2:3]
	global_load_dwordx4 v[44:47], v171, s[2:3]
	global_load_dwordx4 v[48:51], v172, s[2:3]
	global_load_dwordx4 v[52:55], v173, s[2:3]
	global_load_dwordx4 v[56:59], v174, s[2:3]
	global_load_dwordx4 v[60:63], v175, s[2:3]
	s_add_u32 s37, s36, s21
	s_min_u32 s37, s37, 0x3fff
	s_lshl_b32 s34, s37, 9
	s_add_u32 s22, s6, s34
	s_addc_u32 s23, s7, 0
	global_load_dwordx4 v[234:237], v181, s[22:23] offset:0
	global_load_dwordx4 v[238:241], v181, s[22:23] offset:16
	global_load_dwordx4 v[242:245], v181, s[22:23] offset:32
	global_load_dwordx4 v[246:249], v181, s[22:23] offset:48
	global_load_dword v185, v180, s[22:23]

.LBB0_1117:
	s_or_b64 exec, exec, s[0:1]
	s_waitcnt lgkmcnt(0)
	v_mov_b32_e32 v0, v178
	s_barrier
	v_readlane_b32 s2, v255, 3
	v_ashrrev_i32_e32 v1, 6, v0
	s_movk_i32 s16, 0x4000
	v_add_u32_e32 v152, s2, v1
	s_mov_b64 s[6:7], 0
	s_mov_b64 s[0:1], 0
	v_cmp_gt_i32_e32 vcc, s16, v152
	s_and_saveexec_b64 s[8:9], vcc
	s_cbranch_execz .LBB0_1126
	v_readlane_b32 s0, v254, 0
	v_readlane_b32 s1, v254, 1
	v_readlane_b32 s34, v255, 4
	s_lshl_b32 s35, s34, 21
	s_add_u32 s2, s0, 0x4120000
	s_addc_u32 s3, s1, 0
	s_add_u32 s2, s2, s35
	s_addc_u32 s3, s3, 0
	v_readlane_b32 s4, v254, 39
	v_readlane_b32 s5, v254, 40
	s_lshl_b32 s35, s34, 9
	s_add_u32 s4, s4, s35
	s_addc_u32 s5, s5, 0
	s_add_u32 s6, s0, 0x19d20000
	s_addc_u32 s7, s1, 0
	s_lshl_b32 s35, s34, 23
	s_add_u32 s12, s0, 0x10120000
	s_addc_u32 s13, s1, 0
	s_add_u32 s12, s12, s35
	s_addc_u32 s13, s13, 0
	v_readfirstlane_b32 s20, v178
	s_lshr_b32 s20, s20, 6
	v_readlane_b32 s35, v255, 3
	s_add_u32 s20, s20, s35
	s_and_b32 s21, s90, -8
	v_and_b32_e32 v176, 7, v179
	v_lshlrev_b32_e32 v177, 6, v176
	v_lshlrev_b32_e32 v176, 4, v176
	v_lshlrev_b32_e32 v180, 3, v179
	v_lshrrev_b32_e32 v181, 3, v179
	v_lshlrev_b32_e32 v181, 6, v181
	s_mov_b32 s26, 0xcccccccc
	s_mov_b32 s27, 0xcccccccc
	s_mov_b32 s28, 0xaaaaaaaa
	s_mov_b32 s29, 0xaaaaaaaa
	s_lshl_b32 s34, s20, 9
	s_add_u32 s22, s6, s34
	s_addc_u32 s23, s7, 0
	global_load_dwordx4 v[160:163], v181, s[22:23] offset:0
	global_load_dwordx4 v[164:167], v181, s[22:23] offset:16
	global_load_dwordx4 v[168:171], v181, s[22:23] offset:32
	global_load_dwordx4 v[172:175], v181, s[22:23] offset:48
	s_add_u32 s36, s20, s21
	s_min_u32 s36, s36, 0x3fff
	s_lshl_b32 s34, s36, 9
	s_add_u32 s22, s6, s34
	s_addc_u32 s23, s7, 0
	global_load_dwordx4 v[186:189], v181, s[22:23] offset:0
	global_load_dwordx4 v[190:193], v181, s[22:23] offset:16
	global_load_dwordx4 v[194:197], v181, s[22:23] offset:32
	global_load_dwordx4 v[198:201], v181, s[22:23] offset:48
	s_waitcnt vmcnt(0)
	v_lshl_or_b32 v160, v160, 7, v176
	v_lshl_or_b32 v161, v161, 7, v176
	v_lshl_or_b32 v162, v162, 7, v176
	v_lshl_or_b32 v163, v163, 7, v176
	v_lshl_or_b32 v164, v164, 7, v176
	v_lshl_or_b32 v165, v165, 7, v176
	v_lshl_or_b32 v166, v166, 7, v176
	v_lshl_or_b32 v167, v167, 7, v176
	v_lshl_or_b32 v168, v168, 7, v176
	v_lshl_or_b32 v169, v169, 7, v176
	v_lshl_or_b32 v170, v170, 7, v176
	v_lshl_or_b32 v171, v171, 7, v176
	v_lshl_or_b32 v172, v172, 7, v176
	v_lshl_or_b32 v173, v173, 7, v176
	v_lshl_or_b32 v174, v174, 7, v176
	v_lshl_or_b32 v175, v175, 7, v176
	s_lshl_b32 s34, s20, 12
	s_add_u32 s24, s4, s34
	s_addc_u32 s25, s5, 0
	global_load_dwordx4 v[128:131], v177, s[24:25] offset:0
	global_load_dwordx4 v[132:135], v177, s[24:25] offset:16
	global_load_dwordx4 v[136:139], v177, s[24:25] offset:32
	global_load_dwordx4 v[140:143], v177, s[24:25] offset:48
	global_load_dwordx4 v[0:3], v160, s[2:3]
	global_load_dwordx4 v[4:7], v161, s[2:3]
	global_load_dwordx4 v[8:11], v162, s[2:3]
	global_load_dwordx4 v[12:15], v163, s[2:3]
	global_load_dwordx4 v[16:19], v164, s[2:3]
	global_load_dwordx4 v[20:23], v165, s[2:3]
	global_load_dwordx4 v[24:27], v166, s[2:3]
	global_load_dwordx4 v[28:31], v167, s[2:3]
	global_load_dwordx4 v[32:35], v168, s[2:3]
	global_load_dwordx4 v[36:39], v169, s[2:3]
	global_load_dwordx4 v[40:43], v170, s[2:3]
	global_load_dwordx4 v[44:47], v171, s[2:3]
	global_load_dwordx4 v[48:51], v172, s[2:3]
	global_load_dwordx4 v[52:55], v173, s[2:3]
	global_load_dwordx4 v[56:59], v174, s[2:3]
	global_load_dwordx4 v[60:63], v175, s[2:3]
	s_add_u32 s37, s36, s21
	s_min_u32 s37, s37, 0x3fff
	s_lshl_b32 s34, s37, 9
	s_add_u32 s22, s6, s34
	s_addc_u32 s23, s7, 0
	global_load_dwordx4 v[234:237], v181, s[22:23] offset:0
	global_load_dwordx4 v[238:241], v181, s[22:23] offset:16
	global_load_dwordx4 v[242:245], v181, s[22:23] offset:32
	global_load_dwordx4 v[246:249], v181, s[22:23] offset:48
	global_load_dword v185, v180, s[22:23]
